# row-scale prefetch moved out of line: the K-loop pays one compare and an untaken branch per iteration, the loads are issued from the last iteration only
# speedup vs baseline: 1.0056x; 1.0056x over previous
.LBB0_625:
	s_add_i32 s35, s34, 2
	s_add_u32 s56, s6, 0x80
	s_addc_u32 s57, s7, 0
	s_add_i32 s95, 0, 0x10000
	s_cmp_eq_u32 s27, s34
	s_cselect_b32 s57, s39, s57
	s_cselect_b32 s56, s38, s56
	s_cselect_b32 s75, s13, s2
	s_cselect_b32 s74, s12, s1
	s_add_i32 s34, 0, 0x14000
	v_add_u32_e32 v140, s95, v217
	v_add_u32_e32 v156, s34, v217
	s_waitcnt lgkmcnt(0)
	ds_read_b128 v[128:131], v140
	ds_read_b128 v[132:135], v140 offset:1024
	ds_read_b128 v[136:139], v140 offset:2048
	ds_read_b128 v[140:143], v140 offset:3072
	ds_read_b128 v[144:147], v156
	ds_read_b128 v[148:151], v156 offset:1024
	ds_read_b128 v[152:155], v156 offset:2048
	ds_read_b128 v[170:173], v156 offset:3072
	v_lshl_add_u64 v[234:235], s[6:7], 0, v[166:167]
	s_add_i32 m0, s44, 0xc000
	ds_read_b128 v[174:177], v220
	ds_read_b128 v[178:181], v220 offset:1024
	ds_read_b128 v[182:185], v220 offset:2048
	ds_read_b128 v[186:189], v220 offset:3072
	ds_read_b128 v[190:193], v220 offset:4096
	ds_read_b128 v[222:225], v220 offset:5120
	ds_read_b128 v[226:229], v220 offset:6144
	ds_read_b128 v[230:233], v220 offset:7168
	global_load_lds_dwordx4 v[234:235], off
	v_lshl_add_u64 v[234:235], s[6:7], 0, v[168:169]
	s_add_i32 m0, s44, 0xe000
	s_nop 0
	global_load_lds_dwordx4 v[234:235], off
	s_waitcnt vmcnt(8)
	s_waitcnt lgkmcnt(0)
	s_barrier
	s_setprio 1
	s_waitcnt lgkmcnt(0)
	v_mfma_f32_16x16x32_bf16 v[120:123], v[128:131], v[174:177], v[120:123]
	v_mfma_f32_16x16x32_bf16 v[112:115], v[136:139], v[174:177], v[112:115]
	v_mfma_f32_16x16x32_bf16 v[104:107], v[128:131], v[182:185], v[104:107]
	v_mfma_f32_16x16x32_bf16 v[96:99], v[136:139], v[182:185], v[96:99]
	v_mfma_f32_16x16x32_bf16 v[88:91], v[128:131], v[190:193], v[88:91]
	v_mfma_f32_16x16x32_bf16 v[80:83], v[136:139], v[190:193], v[80:83]
	v_mfma_f32_16x16x32_bf16 v[72:75], v[128:131], v[226:229], v[72:75]
	v_mfma_f32_16x16x32_bf16 v[64:67], v[136:139], v[226:229], v[64:67]
	v_mfma_f32_16x16x32_bf16 v[120:123], v[132:135], v[178:181], v[120:123]
	v_mfma_f32_16x16x32_bf16 v[112:115], v[140:143], v[178:181], v[112:115]
	v_mfma_f32_16x16x32_bf16 v[104:107], v[132:135], v[186:189], v[104:107]
	v_mfma_f32_16x16x32_bf16 v[96:99], v[140:143], v[186:189], v[96:99]
	v_mfma_f32_16x16x32_bf16 v[88:91], v[132:135], v[222:225], v[88:91]
	v_mfma_f32_16x16x32_bf16 v[80:83], v[140:143], v[222:225], v[80:83]
	v_mfma_f32_16x16x32_bf16 v[72:75], v[132:135], v[230:233], v[72:75]
	v_mfma_f32_16x16x32_bf16 v[64:67], v[140:143], v[230:233], v[64:67]
	s_setprio 0
	s_setprio 1
	v_mfma_f32_16x16x32_bf16 v[124:127], v[144:147], v[174:177], v[124:127]
	v_mfma_f32_16x16x32_bf16 v[116:119], v[152:155], v[174:177], v[116:119]
	v_mfma_f32_16x16x32_bf16 v[108:111], v[144:147], v[182:185], v[108:111]
	v_mfma_f32_16x16x32_bf16 v[100:103], v[152:155], v[182:185], v[100:103]
	v_mfma_f32_16x16x32_bf16 v[92:95], v[144:147], v[190:193], v[92:95]
	v_mfma_f32_16x16x32_bf16 v[84:87], v[152:155], v[190:193], v[84:87]
	v_mfma_f32_16x16x32_bf16 v[76:79], v[144:147], v[226:229], v[76:79]
	v_mfma_f32_16x16x32_bf16 v[68:71], v[152:155], v[226:229], v[68:71]
	v_mfma_f32_16x16x32_bf16 v[124:127], v[148:151], v[178:181], v[124:127]
	v_mfma_f32_16x16x32_bf16 v[116:119], v[170:173], v[178:181], v[116:119]
	v_mfma_f32_16x16x32_bf16 v[108:111], v[148:151], v[186:189], v[108:111]
	v_mfma_f32_16x16x32_bf16 v[100:103], v[170:173], v[186:189], v[100:103]
	v_mfma_f32_16x16x32_bf16 v[92:95], v[148:151], v[222:225], v[92:95]
	v_mfma_f32_16x16x32_bf16 v[84:87], v[170:173], v[222:225], v[84:87]
	v_mfma_f32_16x16x32_bf16 v[76:79], v[148:151], v[230:233], v[76:79]
	v_mfma_f32_16x16x32_bf16 v[68:71], v[170:173], v[230:233], v[68:71]
	s_setprio 0
	s_barrier
	s_add_i32 s95, s95, s17
	v_lshl_add_u64 v[234:235], s[74:75], 0, v[164:165]
	s_mov_b32 m0, s95
	ds_read_b128 v[174:177], v220 offset:16384
	ds_read_b128 v[178:181], v220 offset:17408
	ds_read_b128 v[182:185], v220 offset:18432
	ds_read_b128 v[186:189], v220 offset:19456
	ds_read_b128 v[190:193], v220 offset:20480
	ds_read_b128 v[222:225], v220 offset:21504
	ds_read_b128 v[226:229], v220 offset:22528
	ds_read_b128 v[230:233], v220 offset:23552
	global_load_lds_dwordx4 v[234:235], off
	s_add_i32 m0, s95, 0x2000
	v_lshl_add_u64 v[236:237], s[74:75], 0, v[160:161]
	s_add_u32 s74, s74, s24
	s_addc_u32 s75, s75, s25
	s_add_i32 s34, s34, s17
	global_load_lds_dwordx4 v[236:237], off
	v_lshl_add_u64 v[238:239], s[74:75], 0, v[164:165]
	s_mov_b32 m0, s34
	v_lshl_add_u64 v[240:241], s[74:75], 0, v[160:161]
	global_load_lds_dwordx4 v[238:239], off
	s_add_i32 m0, s34, 0x2000
	v_lshl_add_u64 v[242:243], s[56:57], 0, v[162:163]
	global_load_lds_dwordx4 v[240:241], off
	s_mov_b32 m0, s44
	v_lshl_add_u64 v[244:245], s[56:57], 0, v[158:159]
	global_load_lds_dwordx4 v[242:243], off
	s_mov_b32 m0, s93
	s_nop 0
	global_load_lds_dwordx4 v[244:245], off
	s_waitcnt vmcnt(8)
	s_waitcnt lgkmcnt(0)
	s_barrier
	s_setprio 1
	s_waitcnt lgkmcnt(0)
	v_mfma_f32_16x16x32_bf16 v[56:59], v[128:131], v[174:177], v[56:59]
	v_mfma_f32_16x16x32_bf16 v[48:51], v[136:139], v[174:177], v[48:51]
	v_mfma_f32_16x16x32_bf16 v[40:43], v[128:131], v[182:185], v[40:43]
	v_mfma_f32_16x16x32_bf16 v[32:35], v[136:139], v[182:185], v[32:35]
	v_mfma_f32_16x16x32_bf16 v[24:27], v[128:131], v[190:193], v[24:27]
	v_mfma_f32_16x16x32_bf16 v[16:19], v[136:139], v[190:193], v[16:19]
	v_mfma_f32_16x16x32_bf16 v[8:11], v[128:131], v[226:229], v[8:11]
	v_mfma_f32_16x16x32_bf16 v[0:3], v[136:139], v[226:229], v[0:3]
	v_mfma_f32_16x16x32_bf16 v[56:59], v[132:135], v[178:181], v[56:59]
	v_mfma_f32_16x16x32_bf16 v[48:51], v[140:143], v[178:181], v[48:51]
	v_mfma_f32_16x16x32_bf16 v[40:43], v[132:135], v[186:189], v[40:43]
	v_mfma_f32_16x16x32_bf16 v[32:35], v[140:143], v[186:189], v[32:35]
	v_mfma_f32_16x16x32_bf16 v[24:27], v[132:135], v[222:225], v[24:27]
	v_mfma_f32_16x16x32_bf16 v[16:19], v[140:143], v[222:225], v[16:19]
	v_mfma_f32_16x16x32_bf16 v[8:11], v[132:135], v[230:233], v[8:11]
	v_mfma_f32_16x16x32_bf16 v[0:3], v[140:143], v[230:233], v[0:3]
	s_setprio 0
	s_setprio 1
	v_mfma_f32_16x16x32_bf16 v[60:63], v[144:147], v[174:177], v[60:63]
	v_mfma_f32_16x16x32_bf16 v[52:55], v[152:155], v[174:177], v[52:55]
	v_mfma_f32_16x16x32_bf16 v[44:47], v[144:147], v[182:185], v[44:47]
	v_mfma_f32_16x16x32_bf16 v[36:39], v[152:155], v[182:185], v[36:39]
	v_mfma_f32_16x16x32_bf16 v[28:31], v[144:147], v[190:193], v[28:31]
	v_mfma_f32_16x16x32_bf16 v[20:23], v[152:155], v[190:193], v[20:23]
	v_mfma_f32_16x16x32_bf16 v[12:15], v[144:147], v[226:229], v[12:15]
	v_mfma_f32_16x16x32_bf16 v[4:7], v[152:155], v[226:229], v[4:7]
	v_mfma_f32_16x16x32_bf16 v[60:63], v[148:151], v[178:181], v[60:63]
	v_mfma_f32_16x16x32_bf16 v[52:55], v[170:173], v[178:181], v[52:55]
	v_mfma_f32_16x16x32_bf16 v[44:47], v[148:151], v[186:189], v[44:47]
	v_mfma_f32_16x16x32_bf16 v[36:39], v[170:173], v[186:189], v[36:39]
	v_mfma_f32_16x16x32_bf16 v[28:31], v[148:151], v[222:225], v[28:31]
	v_mfma_f32_16x16x32_bf16 v[20:23], v[170:173], v[222:225], v[20:23]
	v_mfma_f32_16x16x32_bf16 v[12:15], v[148:151], v[230:233], v[12:15]
	v_mfma_f32_16x16x32_bf16 v[4:7], v[170:173], v[230:233], v[4:7]
	s_setprio 0
	s_barrier
	s_add_i32 s34, 0, 0x18000
	s_add_i32 s74, 0, 0x1c000
	v_add_u32_e32 v140, s34, v217
	v_add_u32_e32 v156, s74, v217
	ds_read_b128 v[128:131], v140
	ds_read_b128 v[132:135], v140 offset:1024
	ds_read_b128 v[136:139], v140 offset:2048
	ds_read_b128 v[140:143], v140 offset:3072
	ds_read_b128 v[144:147], v156
	ds_read_b128 v[148:151], v156 offset:1024
	ds_read_b128 v[152:155], v156 offset:2048
	ds_read_b128 v[170:173], v156 offset:3072
	s_add_u32 s56, s56, s24
	s_addc_u32 s57, s57, s25
	s_mov_b32 m0, s8
	v_lshl_add_u64 v[246:247], s[56:57], 0, v[162:163]
	ds_read_b128 v[174:177], v220 offset:32768
	ds_read_b128 v[178:181], v220 offset:33792
	ds_read_b128 v[182:185], v220 offset:34816
	ds_read_b128 v[186:189], v220 offset:35840
	ds_read_b128 v[190:193], v220 offset:36864
	ds_read_b128 v[222:225], v220 offset:37888
	ds_read_b128 v[226:229], v220 offset:38912
	ds_read_b128 v[230:233], v220 offset:39936
	global_load_lds_dwordx4 v[246:247], off
	v_lshl_add_u64 v[246:247], s[56:57], 0, v[158:159]
	s_mov_b32 m0, s55
	s_nop 0
	global_load_lds_dwordx4 v[246:247], off
	s_waitcnt vmcnt(8)
	s_waitcnt lgkmcnt(0)
	s_barrier
	s_setprio 1
	s_waitcnt lgkmcnt(0)
	v_mfma_f32_16x16x32_bf16 v[120:123], v[128:131], v[174:177], v[120:123]
	v_mfma_f32_16x16x32_bf16 v[112:115], v[136:139], v[174:177], v[112:115]
	v_mfma_f32_16x16x32_bf16 v[104:107], v[128:131], v[182:185], v[104:107]
	v_mfma_f32_16x16x32_bf16 v[96:99], v[136:139], v[182:185], v[96:99]
	v_mfma_f32_16x16x32_bf16 v[88:91], v[128:131], v[190:193], v[88:91]
	v_mfma_f32_16x16x32_bf16 v[80:83], v[136:139], v[190:193], v[80:83]
	v_mfma_f32_16x16x32_bf16 v[72:75], v[128:131], v[226:229], v[72:75]
	v_mfma_f32_16x16x32_bf16 v[64:67], v[136:139], v[226:229], v[64:67]
	v_mfma_f32_16x16x32_bf16 v[120:123], v[132:135], v[178:181], v[120:123]
	v_mfma_f32_16x16x32_bf16 v[112:115], v[140:143], v[178:181], v[112:115]
	v_mfma_f32_16x16x32_bf16 v[104:107], v[132:135], v[186:189], v[104:107]
	v_mfma_f32_16x16x32_bf16 v[96:99], v[140:143], v[186:189], v[96:99]
	v_mfma_f32_16x16x32_bf16 v[88:91], v[132:135], v[222:225], v[88:91]
	v_mfma_f32_16x16x32_bf16 v[80:83], v[140:143], v[222:225], v[80:83]
	v_mfma_f32_16x16x32_bf16 v[72:75], v[132:135], v[230:233], v[72:75]
	v_mfma_f32_16x16x32_bf16 v[64:67], v[140:143], v[230:233], v[64:67]
	s_setprio 0
	s_setprio 1
	v_mfma_f32_16x16x32_bf16 v[124:127], v[144:147], v[174:177], v[124:127]
	v_mfma_f32_16x16x32_bf16 v[116:119], v[152:155], v[174:177], v[116:119]
	v_mfma_f32_16x16x32_bf16 v[108:111], v[144:147], v[182:185], v[108:111]
	v_mfma_f32_16x16x32_bf16 v[100:103], v[152:155], v[182:185], v[100:103]
	v_mfma_f32_16x16x32_bf16 v[92:95], v[144:147], v[190:193], v[92:95]
	v_mfma_f32_16x16x32_bf16 v[84:87], v[152:155], v[190:193], v[84:87]
	v_mfma_f32_16x16x32_bf16 v[76:79], v[144:147], v[226:229], v[76:79]
	v_mfma_f32_16x16x32_bf16 v[68:71], v[152:155], v[226:229], v[68:71]
	v_mfma_f32_16x16x32_bf16 v[124:127], v[148:151], v[178:181], v[124:127]
	v_mfma_f32_16x16x32_bf16 v[116:119], v[170:173], v[178:181], v[116:119]
	v_mfma_f32_16x16x32_bf16 v[108:111], v[148:151], v[186:189], v[108:111]
	v_mfma_f32_16x16x32_bf16 v[100:103], v[170:173], v[186:189], v[100:103]
	v_mfma_f32_16x16x32_bf16 v[92:95], v[148:151], v[222:225], v[92:95]
	v_mfma_f32_16x16x32_bf16 v[84:87], v[170:173], v[222:225], v[84:87]
	v_mfma_f32_16x16x32_bf16 v[76:79], v[148:151], v[230:233], v[76:79]
	v_mfma_f32_16x16x32_bf16 v[68:71], v[170:173], v[230:233], v[68:71]
	s_setprio 0
	s_barrier
	s_add_i32 s34, s34, s17
	v_lshl_add_u64 v[234:235], v[234:235], 0, s[52:53]
	s_mov_b32 m0, s34
	ds_read_b128 v[174:177], v220 offset:49152
	ds_read_b128 v[178:181], v220 offset:50176
	ds_read_b128 v[182:185], v220 offset:51200
	ds_read_b128 v[186:189], v220 offset:52224
	ds_read_b128 v[190:193], v220 offset:53248
	ds_read_b128 v[222:225], v220 offset:54272
	ds_read_b128 v[226:229], v220 offset:55296
	ds_read_b128 v[230:233], v220 offset:56320
	global_load_lds_dwordx4 v[234:235], off
	v_lshl_add_u64 v[234:235], v[236:237], 0, s[52:53]
	s_add_i32 m0, s34, 0x2000
	s_add_i32 s34, s74, s17
	global_load_lds_dwordx4 v[234:235], off
	v_lshl_add_u64 v[234:235], v[238:239], 0, s[52:53]
	s_mov_b32 m0, s34
	s_nop 0
	global_load_lds_dwordx4 v[234:235], off
	v_lshl_add_u64 v[234:235], v[240:241], 0, s[52:53]
	s_add_i32 m0, s34, 0x2000
	s_nop 0
	global_load_lds_dwordx4 v[234:235], off
	v_lshl_add_u64 v[234:235], v[242:243], 0, s[52:53]
	s_mov_b32 m0, s9
	s_nop 0
	global_load_lds_dwordx4 v[234:235], off
	v_lshl_add_u64 v[234:235], v[244:245], 0, s[52:53]
	s_mov_b32 m0, s29
	s_nop 0
	global_load_lds_dwordx4 v[234:235], off
	s_waitcnt vmcnt(8)
	s_waitcnt lgkmcnt(0)
	s_barrier
	s_cmp_ge_i32 s35, s49
	s_cbranch_scc1 .Lpf_check

.Lpf_check:
	s_cmp_eq_u32 s47, 0
	s_cbranch_scc1 .Lpf_do
	s_cmp_eq_u32 s47, 1
	s_cbranch_scc0 .Lpf_back
	s_cmp_eq_u64 s[96:97], 0
	s_cbranch_scc1 .Lpf_back
.Lpf_do:
	v_add_u32_e32 v246, s92, v216
	v_lshl_add_u32 v246, s15, 8, v246
	v_ashrrev_i32_e32 v247, 31, v246
	v_lshl_add_u64 v[246:247], v[246:247], 3, s[96:97]
	global_load_dwordx2 v[234:235], v[246:247], off
	global_load_dwordx2 v[236:237], v[246:247], off offset:128
	global_load_dwordx2 v[238:239], v[246:247], off offset:256
	global_load_dwordx2 v[240:241], v[246:247], off offset:384
	global_load_dwordx2 v[242:243], v[246:247], off offset:1024
	global_load_dwordx2 v[244:245], v[246:247], off offset:1152
	global_load_dwordx2 v[250:251], v[246:247], off offset:1280
	global_load_dwordx2 v[252:253], v[246:247], off offset:1408
	s_branch .Lpf_back
